# speedup vs baseline: 1.0022x; 1.0022x over previous
.LBB0_743:
	s_waitcnt vmcnt(0)
	v_mov_b32_e32 v46, v212
	s_lshl_b32 s2, s9, 4
	v_readfirstlane_b32 s0, v46
	s_ashr_i32 s5, s0, 6
	s_ashr_i32 s0, s0, 7
	s_and_b32 s2, s2, 0xffffff80
	s_lshl_b32 s3, s0, 5
	v_and_b32_e32 v219, 31, v46
	s_add_i32 s6, s3, s2
	v_or_b32_e32 v2, s6, v219
	v_ashrrev_i32_e32 v3, 31, v2
	v_readlane_b32 s2, v253, 36
	s_and_b32 s1, s9, 7
	v_lshlrev_b64 v[2:3], 11, v[2:3]
	v_readlane_b32 s3, v253, 37
	s_and_b32 s4, s5, 1
	s_lshl_b32 s42, s1, 8
	v_lshl_add_u64 v[2:3], s[2:3], 0, v[2:3]
	v_bfe_u32 v218, v46, 5, 1
	v_lshl_add_u64 v[2:3], v[2:3], 0, s[42:43]
	s_lshl_b32 s2, s4, 7
	s_mov_b32 s3, s43
	v_lshl_add_u64 v[2:3], v[2:3], 0, s[2:3]
	v_lshlrev_b32_e32 v190, 4, v218
	v_mov_b32_e32 v191, v1
	v_lshl_add_u64 v[2:3], v[2:3], 0, v[190:191]
	global_load_dwordx4 v[160:163], v[2:3], off
	global_load_dwordx4 v[164:167], v[2:3], off offset:32
	global_load_dwordx4 v[34:37], v[2:3], off offset:64
	global_load_dwordx4 v[38:41], v[2:3], off offset:96
	v_ashrrev_i32_e32 v2, 4, v46
	v_ashrrev_i32_e32 v3, 31, v2
	v_readlane_b32 s2, v253, 38
	v_lshlrev_b64 v[4:5], 11, v[2:3]
	v_readlane_b32 s3, v253, 39
	v_bfe_u32 v0, v46, 3, 1
	v_ashrrev_i32_e32 v19, 3, v46
	v_lshl_add_u64 v[4:5], s[2:3], 0, v[4:5]
	s_lshl_b32 s2, s1, 22
	v_readlane_b32 s3, v253, 40
	v_mul_u32_u24_e32 v3, 0x2400, v0
	s_movk_i32 s7, 0x90
	v_lshlrev_b32_e32 v0, 4, v46
	s_add_u32 s2, s3, s2
	v_readlane_b32 s3, v253, 41
	v_lshlrev_b32_e32 v42, 6, v19
	v_and_b32_e32 v48, 15, v46
	v_mul_lo_u32 v2, v2, s7
	v_and_b32_e32 v0, 0x70, v0
	s_addc_u32 s3, s3, 0
	v_ashrrev_i32_e32 v43, 31, v42
	v_lshl_add_u64 v[4:5], v[4:5], 0, s[42:43]
	v_lshlrev_b32_e32 v188, 4, v48
	v_mov_b32_e32 v189, v1
	v_add3_u32 v18, v0, v2, v3
	v_lshl_add_u64 v[2:3], v[42:43], 1, s[2:3]
	s_mul_i32 s2, s4, 0x2400
	v_mad_u32_u24 v47, v219, s7, v190
	v_lshl_add_u64 v[192:193], v[4:5], 0, v[188:189]
	v_add_u32_e32 v20, s2, v47
	s_mov_b32 s2, 0x10000
	v_add_co_u32_e32 v6, vcc, s2, v192
	v_lshl_add_u64 v[194:195], v[2:3], 0, v[0:1]
	global_load_dwordx4 v[2:5], v[192:193], off
	v_addc_co_u32_e32 v7, vcc, 0, v193, vcc
	global_load_dwordx4 v[6:9], v[6:7], off
	s_nop 0
	global_load_dwordx4 v[10:13], v[194:195], off
	v_add_co_u32_e32 v44, vcc, s33, v194
	v_add_u32_e32 v221, 0, v18
	s_nop 0
	v_addc_co_u32_e32 v45, vcc, 0, v195, vcc
	global_load_dwordx4 v[14:17], v[44:45], off
	v_add_u32_e32 v223, 0, v20
	v_and_b32_e32 v217, 63, v46
	v_mov_b64_e32 v[208:209], 0x7ff
	v_mov_b64_e32 v[186:187], 0x800
	s_waitcnt vmcnt(3)
	ds_write_b128 v221, v[2:5]
	s_waitcnt vmcnt(2)
	ds_write_b128 v221, v[6:9] offset:4608
	v_mad_u64_u32 v[2:3], s[2:3], v19, s7, v[0:1]
	s_mov_b32 s2, 0x20000
	v_add_u32_e32 v222, 0, v2
	v_add_co_u32_e32 v2, vcc, s2, v192
	s_mov_b32 s2, 0x30000
	s_nop 0
	v_addc_co_u32_e32 v3, vcc, 0, v193, vcc
	s_waitcnt vmcnt(1)
	ds_write_b128 v222, v[10:13] offset:55296
	s_waitcnt vmcnt(0)
	ds_write_b128 v222, v[14:17] offset:64512
	v_add_co_u32_e32 v6, vcc, s2, v192
	global_load_dwordx4 v[2:5], v[2:3], off
	s_nop 0
	v_addc_co_u32_e32 v7, vcc, 0, v193, vcc
	global_load_dwordx4 v[6:9], v[6:7], off
	s_lshl_b32 s2, s5, 11
	s_add_i32 s2, s2, 0
	s_add_i32 s2, s2, 0x12000
	s_cmp_lt_i32 s5, 4
	s_waitcnt vmcnt(1)
	ds_write_b128 v221, v[2:5] offset:18432
	s_waitcnt vmcnt(0)
	ds_write_b128 v221, v[6:9] offset:23040
	s_waitcnt lgkmcnt(0)
	s_barrier
	ds_read_b128 v[18:21], v223 offset:4608
	ds_read_b128 v[2:5], v223
	ds_read_b128 v[50:53], v223 offset:32
	ds_read_b128 v[54:57], v223 offset:4640
	s_waitcnt lgkmcnt(2)
	v_mfma_f32_32x32x16_bf16 v[2:17], v[2:5], v[160:163], 0
	v_mfma_f32_32x32x16_bf16 v[18:33], v[18:21], v[160:163], 0
	s_waitcnt lgkmcnt(1)
	v_mfma_f32_32x32x16_bf16 v[2:17], v[50:53], v[164:167], v[2:17]
	s_waitcnt lgkmcnt(0)
	v_mfma_f32_32x32x16_bf16 v[18:33], v[54:57], v[164:167], v[18:33]
	ds_read_b128 v[50:53], v223 offset:64
	ds_read_b128 v[54:57], v223 offset:4672
	s_waitcnt lgkmcnt(1)
	v_mfma_f32_32x32x16_bf16 v[2:17], v[50:53], v[34:37], v[2:17]
	s_waitcnt lgkmcnt(0)
	v_mfma_f32_32x32x16_bf16 v[18:33], v[54:57], v[34:37], v[18:33]
	ds_read_b128 v[50:53], v223 offset:96
	ds_read_b128 v[54:57], v223 offset:4704
	s_waitcnt lgkmcnt(1)
	v_mfma_f32_32x32x16_bf16 v[2:17], v[50:53], v[38:41], v[2:17]
	s_waitcnt lgkmcnt(0)
	v_mfma_f32_32x32x16_bf16 v[18:33], v[54:57], v[38:41], v[18:33]
	s_nop 9
	v_max_f32_e32 v49, v3, v3
	v_max_f32_e32 v50, v4, v4
	v_max_f32_e32 v51, v5, v5
	v_max_f32_e32 v0, v19, v19
	v_max_f32_e32 v0, v49, v0
	v_max_f32_e32 v49, v20, v20
	v_max_f32_e32 v49, v50, v49
	v_max_f32_e32 v50, v21, v21
	v_max3_f32 v0, v2, v18, v0
	v_max_f32_e32 v50, v51, v50
	v_max3_f32 v0, v0, v49, v50
	v_max_f32_e32 v49, v22, v22
	v_max_f32_e32 v50, v6, v6
	v_max_f32_e32 v49, v50, v49
	v_max_f32_e32 v50, v23, v23
	v_max_f32_e32 v51, v7, v7
	v_max_f32_e32 v50, v51, v50
	v_max3_f32 v0, v0, v49, v50
	v_max_f32_e32 v49, v24, v24
	v_max_f32_e32 v50, v8, v8
	v_max_f32_e32 v49, v50, v49
	v_max_f32_e32 v50, v25, v25
	v_max_f32_e32 v51, v9, v9
	v_max_f32_e32 v50, v51, v50
	v_max3_f32 v0, v0, v49, v50
	v_max_f32_e32 v49, v26, v26
	v_max_f32_e32 v50, v10, v10
	v_max_f32_e32 v49, v50, v49
	v_max_f32_e32 v50, v27, v27
	v_max_f32_e32 v51, v11, v11
	v_max_f32_e32 v50, v51, v50
	v_max3_f32 v0, v0, v49, v50
	v_max_f32_e32 v49, v28, v28
	v_max_f32_e32 v50, v12, v12
	v_max_f32_e32 v49, v50, v49
	v_max_f32_e32 v50, v29, v29
	v_max_f32_e32 v51, v13, v13
	v_max_f32_e32 v50, v51, v50
	v_max3_f32 v0, v0, v49, v50
	v_max_f32_e32 v49, v30, v30
	v_max_f32_e32 v50, v14, v14
	v_max_f32_e32 v49, v50, v49
	v_max_f32_e32 v50, v31, v31
	v_max_f32_e32 v51, v15, v15
	v_max_f32_e32 v50, v51, v50
	v_max3_f32 v0, v0, v49, v50
	v_max_f32_e32 v49, v32, v32
	v_max_f32_e32 v50, v16, v16
	v_max_f32_e32 v49, v50, v49
	v_max_f32_e32 v50, v33, v33
	v_max_f32_e32 v51, v17, v17
	v_max_f32_e32 v50, v51, v50
	v_max3_f32 v0, v0, v49, v50
	v_and_b32_e32 v50, 64, v215
	v_xor_b32_e32 v49, 32, v215
	v_add_u32_e32 v50, 64, v50
	v_cmp_lt_i32_e32 vcc, v49, v50
	v_lshlrev_b32_e32 v50, 4, v217
	v_add_u32_e32 v224, s2, v50
	v_cndmask_b32_e32 v49, v215, v49, vcc
	ds_write_b128 v224, v[34:37]
	ds_write_b128 v224, v[38:41] offset:1024
	v_add_co_u32_e32 v34, vcc, 0x40000, v192
	v_lshlrev_b32_e32 v189, 2, v49
	s_nop 0
	v_addc_co_u32_e32 v35, vcc, 0, v193, vcc
	global_load_dwordx4 v[128:131], v[34:35], off
	v_add_co_u32_e32 v34, vcc, 0x50000, v192
	ds_bpermute_b32 v49, v189, v0
	s_nop 0
	v_addc_co_u32_e32 v35, vcc, 0, v193, vcc
	global_load_dwordx4 v[144:147], v[34:35], off
	global_load_dwordx4 v[168:171], v[194:195], off
	global_load_dwordx4 v[172:175], v[44:45], off
	s_waitcnt lgkmcnt(0)
	s_barrier
	s_cbranch_scc0 .LBB0_745
	s_setprio 1
